# grid barrier (5 in-loop instances): the per-CU L1 invalidate is issued at arrival (right after the arrival atomic) instead of after the release is observed; no data loads happen in between, so it leav
# speedup vs baseline: 1.0145x; 1.0145x over previous
.LBB0_814:
	s_or_b64 exec, exec, s[6:7]
	s_waitcnt lgkmcnt(1)
	v_cvt_f32_u32_e32 v4, v2
	s_waitcnt vmcnt(0)
	v_readfirstlane_b32 s4, v3
	buffer_inv sc1
	v_sub_u32_e32 v3, 0, v2
	v_rcp_iflag_f32_e32 v4, v4
	v_add_u32_e32 v5, s4, v1
	v_mul_f32_e32 v4, 0x4f7ffffe, v4
	v_cvt_u32_f32_e32 v4, v4
	v_mul_lo_u32 v1, v3, v4
	v_mul_hi_u32 v1, v4, v1
	v_add_u32_e32 v1, v4, v1
	v_mul_hi_u32 v1, v5, v1
	v_mul_lo_u32 v3, v1, v2
	v_sub_u32_e32 v3, v5, v3
	v_add_u32_e32 v4, 1, v1
	v_cmp_ge_u32_e32 vcc, v3, v2
	s_nop 1
	v_cndmask_b32_e32 v1, v1, v4, vcc
	v_sub_u32_e32 v4, v3, v2
	v_cndmask_b32_e32 v3, v3, v4, vcc
	v_add_u32_e32 v4, 1, v1
	v_cmp_ge_u32_e32 vcc, v3, v2
	v_add_u32_e32 v3, 1, v5
	s_nop 0
	v_cndmask_b32_e32 v1, v1, v4, vcc
	v_mul_lo_u32 v4, v2, v1
	v_add_u32_e32 v2, v4, v2
	v_cmp_ne_u32_e32 vcc, v3, v2
	s_and_saveexec_b64 s[4:5], vcc
	s_xor_b64 s[4:5], exec, s[4:5]
	s_cbranch_execz .LBB0_828
	s_add_i32 s96, s20, 0x900
	s_lshl_b64 s[6:7], s[96:97], 2
	v_readlane_b32 s8, v254, 10
	v_readlane_b32 s9, v254, 11
	s_add_u32 s8, s8, s6
	s_addc_u32 s9, s9, s7
	s_waitcnt lgkmcnt(0)
	s_nop 1
	global_load_dword v0, v65, s[8:9] sc1
	s_waitcnt vmcnt(0)
	v_cmp_eq_u32_e32 vcc, v0, v1
	s_and_saveexec_b64 s[6:7], vcc
	s_cbranch_execz .LBB0_827
	s_mov_b32 s21, 1
	s_mov_b64 s[10:11], 0
	s_branch .LBB0_818

.LBB0_827:
	s_or_b64 exec, exec, s[6:7]
	s_waitcnt vmcnt(0)
	s_waitcnt vmcnt(0)

.LBB0_845:
	s_or_b64 exec, exec, s[4:5]
	s_mov_b64 s[4:5], exec
	v_mbcnt_lo_u32_b32 v0, s4, 0
	v_mbcnt_hi_u32_b32 v0, s5, v0
	v_cmp_eq_u32_e32 vcc, 0, v0
	s_waitcnt vmcnt(0)
	s_and_saveexec_b64 s[6:7], vcc
	s_cbranch_execz .LBB0_847
	s_add_i32 s96, s20, 0x900
	s_lshl_b64 s[8:9], s[96:97], 2
	v_readlane_b32 s10, v254, 10
	v_readlane_b32 s11, v254, 11
	s_add_u32 s8, s10, s8
	s_addc_u32 s9, s11, s9
	s_bcnt1_i32_b64 s4, s[4:5]
	v_mov_b32_e32 v0, s4
	global_atomic_add v65, v0, s[8:9]

.LBB0_2082:
	s_or_b64 exec, exec, s[18:19]
	s_waitcnt lgkmcnt(1)
	v_cvt_f32_u32_e32 v4, v2
	s_waitcnt vmcnt(0)
	v_readfirstlane_b32 s0, v3
	buffer_inv sc1
	v_sub_u32_e32 v3, 0, v2
	v_rcp_iflag_f32_e32 v4, v4
	v_add_u32_e32 v5, s0, v1
	v_mul_f32_e32 v4, 0x4f7ffffe, v4
	v_cvt_u32_f32_e32 v4, v4
	v_mul_lo_u32 v1, v3, v4
	v_mul_hi_u32 v1, v4, v1
	v_add_u32_e32 v1, v4, v1
	v_mul_hi_u32 v1, v5, v1
	v_mul_lo_u32 v3, v1, v2
	v_sub_u32_e32 v3, v5, v3
	v_add_u32_e32 v4, 1, v1
	v_cmp_ge_u32_e32 vcc, v3, v2
	s_nop 1
	v_cndmask_b32_e32 v1, v1, v4, vcc
	v_sub_u32_e32 v4, v3, v2
	v_cndmask_b32_e32 v3, v3, v4, vcc
	v_add_u32_e32 v4, 1, v1
	v_cmp_ge_u32_e32 vcc, v3, v2
	v_add_u32_e32 v3, 1, v5
	s_nop 0
	v_cndmask_b32_e32 v1, v1, v4, vcc
	v_mul_lo_u32 v4, v2, v1
	v_add_u32_e32 v2, v4, v2
	v_cmp_ne_u32_e32 vcc, v3, v2
	s_and_saveexec_b64 s[0:1], vcc
	s_xor_b64 s[16:17], exec, s[0:1]
	s_cbranch_execz .LBB0_2096
	s_add_i32 s96, s4, 0x900
	s_lshl_b64 s[0:1], s[96:97], 2
	v_readlane_b32 s8, v254, 10
	v_readlane_b32 s9, v254, 11
	s_add_u32 s20, s8, s0
	s_addc_u32 s21, s9, s1
	s_waitcnt lgkmcnt(0)
	global_load_dword v0, v65, s[20:21] sc1
	s_waitcnt vmcnt(0)
	v_cmp_eq_u32_e32 vcc, v0, v1
	s_and_saveexec_b64 s[18:19], vcc
	s_cbranch_execz .LBB0_2095
	s_mov_b32 s5, 1
	s_mov_b64 s[22:23], 0
	s_branch .LBB0_2086

.LBB0_2095:
	s_or_b64 exec, exec, s[18:19]
	s_waitcnt vmcnt(0)
	s_waitcnt vmcnt(0)

.LBB0_2113:
	s_or_b64 exec, exec, s[16:17]
	s_mov_b64 s[16:17], exec
	v_mbcnt_lo_u32_b32 v0, s16, 0
	v_mbcnt_hi_u32_b32 v0, s17, v0
	v_cmp_eq_u32_e32 vcc, 0, v0
	s_waitcnt vmcnt(0)
	s_and_saveexec_b64 s[18:19], vcc
	s_cbranch_execz .LBB0_2115
	s_add_i32 s96, s4, 0x900
	s_lshl_b64 s[0:1], s[96:97], 2
	v_readlane_b32 s4, v254, 10
	v_readlane_b32 s5, v254, 11
	s_add_u32 s0, s4, s0
	s_addc_u32 s1, s5, s1
	s_bcnt1_i32_b64 s4, s[16:17]
	v_mov_b32_e32 v0, s4
	global_atomic_add v65, v0, s[0:1]

.LBB0_2135:
	s_or_b64 exec, exec, s[20:21]
	s_waitcnt lgkmcnt(1)
	v_cvt_f32_u32_e32 v4, v2
	s_waitcnt vmcnt(0)
	v_readfirstlane_b32 s0, v3
	buffer_inv sc1
	v_sub_u32_e32 v3, 0, v2
	v_rcp_iflag_f32_e32 v4, v4
	v_add_u32_e32 v5, s0, v1
	v_mul_f32_e32 v4, 0x4f7ffffe, v4
	v_cvt_u32_f32_e32 v4, v4
	v_mul_lo_u32 v1, v3, v4
	v_mul_hi_u32 v1, v4, v1
	v_add_u32_e32 v1, v4, v1
	v_mul_hi_u32 v1, v5, v1
	v_mul_lo_u32 v3, v1, v2
	v_sub_u32_e32 v3, v5, v3
	v_add_u32_e32 v4, 1, v1
	v_cmp_ge_u32_e32 vcc, v3, v2
	s_nop 1
	v_cndmask_b32_e32 v1, v1, v4, vcc
	v_sub_u32_e32 v4, v3, v2
	v_cndmask_b32_e32 v3, v3, v4, vcc
	v_add_u32_e32 v4, 1, v1
	v_cmp_ge_u32_e32 vcc, v3, v2
	v_add_u32_e32 v3, 1, v5
	s_nop 0
	v_cndmask_b32_e32 v1, v1, v4, vcc
	v_mul_lo_u32 v4, v2, v1
	v_add_u32_e32 v2, v4, v2
	v_cmp_ne_u32_e32 vcc, v3, v2
	s_and_saveexec_b64 s[0:1], vcc
	s_xor_b64 s[18:19], exec, s[0:1]
	s_cbranch_execz .LBB0_2149
	s_add_i32 s96, s4, 0x900
	s_lshl_b64 s[0:1], s[96:97], 2
	v_readlane_b32 s8, v254, 10
	v_readlane_b32 s9, v254, 11
	s_add_u32 s22, s8, s0
	s_addc_u32 s23, s9, s1
	s_waitcnt lgkmcnt(0)
	global_load_dword v0, v65, s[22:23] sc1
	s_waitcnt vmcnt(0)
	v_cmp_eq_u32_e32 vcc, v0, v1
	s_and_saveexec_b64 s[20:21], vcc
	s_cbranch_execz .LBB0_2148
	s_mov_b32 s5, 1
	s_mov_b64 s[24:25], 0
	s_branch .LBB0_2139

.LBB0_2148:
	s_or_b64 exec, exec, s[20:21]
	s_waitcnt vmcnt(0)
	s_waitcnt vmcnt(0)

.LBB0_2166:
	s_or_b64 exec, exec, s[18:19]
	s_mov_b64 s[18:19], exec
	v_mbcnt_lo_u32_b32 v0, s18, 0
	v_mbcnt_hi_u32_b32 v0, s19, v0
	v_cmp_eq_u32_e32 vcc, 0, v0
	s_waitcnt vmcnt(0)
	s_and_saveexec_b64 s[20:21], vcc
	s_cbranch_execz .LBB0_2168
	s_add_i32 s96, s4, 0x900
	s_lshl_b64 s[0:1], s[96:97], 2
	v_readlane_b32 s4, v254, 10
	v_readlane_b32 s5, v254, 11
	s_add_u32 s0, s4, s0
	s_addc_u32 s1, s5, s1
	s_bcnt1_i32_b64 s4, s[18:19]
	v_mov_b32_e32 v0, s4
	global_atomic_add v65, v0, s[0:1]

.LBB0_2308:
	s_or_b64 exec, exec, s[4:5]
	s_mov_b64 s[4:5], exec
	v_mbcnt_lo_u32_b32 v0, s4, 0
	v_mbcnt_hi_u32_b32 v0, s5, v0
	v_cmp_eq_u32_e32 vcc, 0, v0
	s_waitcnt vmcnt(0)
	s_and_saveexec_b64 s[6:7], vcc
	s_cbranch_execnz .LBB0_2309
	s_getpc_b64 s[98:99]
